# v2 + static s_setprio 1 for waves 4-7 during the mixed attention phase
# baseline (speedup 1.0000x reference)
;     unsigned char* ws = a.ws;
;     const bf16* PROJ = (const bf16*)(ws + WS_PROJ); const bf16* QB = (const bf16*)(ws + WS_QB); const bf16* KVB = (const bf16*)(ws + WS_KVB); const bf16* KR = (const bf16*)(ws + WS_KR);
;     bf16* OB = (bf16*)(ws + WS_OB);
; #pragma unroll 1
;     for (int ui = blockIdx.x; ui < 1024; ui += gridDim.x) {
;         if ((skip == 1 && ui < 512) || (skip == 2 && ui >= 512)) continue;
;         if (ui < 512) {
; __global__ void __launch_bounds__(NWAVES * 64) mega_fwd(Args a) {
;     ...
;         else if (kind == 3) attn_mix_phase(a, (char*)lds, l);
.LBB0_202:
	s_andn2_b64 vcc, exec, s[4:5]
	s_cbranch_vccnz .LBB0_289
	v_readlane_b32 s2, v250, 2
	v_readlane_b32 s3, v250, 3
	s_andn2_b64 vcc, exec, s[2:3]
	s_cbranch_vccnz .LBB0_289
	v_readfirstlane_b32 s2, v198
	s_nop 3
	s_cmpk_lt_u32 s2, 0x100
	s_cbranch_scc1 .Lprio_att_done
	s_setprio 1
.Lprio_att_done:
	s_lshl_b32 s31, s22, 3
	v_readlane_b32 s35, v249, 24
	v_readlane_b32 s48, v249, 23
	v_readlane_b32 s49, v249, 22
	v_readlane_b32 s54, v251, 0
	v_writelane_b32 v248, s22, 25
	s_branch .LBB0_207

;     ...
; #pragma unroll 1
;     for (int ui = blockIdx.x; ui < 1024; ui += gridDim.x) {
;         if ((skip == 1 && ui < 512) || (skip == 2 && ui >= 512)) continue;
;         if (ui < 512) {
;             const int half = ui >> 8, it = ui & 255, xcd = it & 7, slot = it >> 3, bh = xcd * 4 + (slot >> 3), p = slot & 7, qb = half ? p : 15 - p, b = bh >> 3, h = bh & 7;
;             const size_t qrow = (size_t)b * SEQ + 256 * qb, krow = (size_t)b * SEQ;
;     ...
;             att::attn_unit<2>(lds, QB + qrow * QW + h * 128, QB + qrow * QW + 1024 + h * 64, KVB + krow * KVW + h * 128, KVB + krow * KVW + 1024 + h * 128, KR + krow * 64,
;                               OB + qrow * DM + 1024 + h * 128, QW, QW, KVW, DM, 4 * qb + 4, 4 * qb, 0, nullptr);
;     ...
;         } else {
;             const int it = ui - 512, xcd = it & 7, slot = it >> 3, bh = xcd * 4 + (slot >> 4), qb = slot & 15, b = bh >> 3, h = bh & 7;
;             const int qc0 = 4 * qb, kc0 = qc0 > 8 ? qc0 - 8 : 0;
;             const size_t qrow = (size_t)b * SEQ + 256 * qb, krow = (size_t)b * SEQ + 64 * kc0;
;     ...
;             att::attn_unit<1>(lds, PROJ + qrow * INP + h * 128, nullptr, PROJ + krow * INP + 1024 + h * 128, PROJ + krow * INP + 2048 + h * 128, nullptr,
;                               OB + qrow * DM + h * 128, INP, 0, INP, DM, qc0 + 4 - kc0, qc0, kc0, (const float*)a.in[5] + ((size_t)l * 8 + h) * 257);
;     ...
;         }
;     }
.LBB0_288:
	s_setprio 0
	v_readlane_b32 s48, v249, 36
	v_readlane_b32 s54, v249, 38
	v_readlane_b32 s49, v249, 37
	v_readlane_b32 s55, v249, 39
	v_readlane_b32 s35, v249, 40
	v_readlane_b32 s22, v248, 25
